# item dispatch: alternate two LDS slots for the popped index and drop the second s_barrier of every work-queue pop
# baseline (speedup 1.0000x reference)
; template <int DQK, bool SB, bool SMAX>
; DI void attn_item(const Params& p, char* smem, int bh, int qb, float Mb) {
;     ...
;   bf16x8 tri[2], ones;
; #pragma unroll
;   for (int s = 0; s < 2; ++s)
; #pragma unroll
;     for (int j = 0; j < 8; ++j) tri[s][j] = ((16 * s + 8 * (j >> 2) + 4 * h + (j & 3)) >= r) ? (short)0x3F80 : (short)0;
; #pragma unroll
;   for (int j = 0; j < 8; ++j) ones[j] = (short)0x3F80;
;   const int nt = 2 * (qb + 1);
;   f32x16 O[2];
; #pragma unroll
;   for (int db = 0; db < 2; ++db)
; #pragma unroll
;     for (int i = 0; i < 16; ++i) O[db][i] = 0.f;
;   float m = -__builtin_huge_valf(), lsum = 0.f, carry = 0.f;
;   f32x16 negM;
; #pragma unroll
;   for (int i = 0; i < 16; ++i) negM[i] = -Mb;
; DI void phase4(const Params& p, char* smem, const Sched sc) {
;     ...
;   float gq = 0.f, gk = 0.f;
;   for (int i = 0; i < 96; ++i) { gq = fmaxf(gq, fabsf(p.qhn[i])); gk = fmaxf(gk, fabsf(p.khn[i])); }
;   const float Mb = LOG2E * 9.797958971132712f * gq * gk * 1.02f;
;   const bool smax = Mb < 56.f;
.LBB0_417:
	s_or_b64 exec, exec, s[0:1]
	s_waitcnt lgkmcnt(0)
	s_barrier
	v_mov_b32_e32 v1, v215
	v_mov_b32_e32 v2, v216
	v_readlane_b32 s0, v255, 5
	v_readlane_b32 s1, v255, 6
	s_and_b64 vcc, exec, s[0:1]
	s_cbranch_vccnz .LBB0_487
	v_lshlrev_b32_e32 v197, 2, v171
	v_mul_f32_e32 v0, 0x41622ae0, v1
	v_mov_b32_e32 v1, 0x3f80
	v_cmp_lt_u32_e32 vcc, v197, v226
	v_or_b32_e32 v4, 1, v197
	v_mul_f32_e32 v0, v2, v0
	v_cndmask_b32_e64 v2, v1, 0, vcc
	v_or_b32_e32 v3, 2, v197
	v_cmp_lt_u32_e32 vcc, v4, v226
	v_or_b32_e32 v6, 3, v197
	v_or_b32_e32 v5, 8, v197
	v_cndmask_b32_e64 v4, v1, 0, vcc
	v_cmp_lt_u32_e32 vcc, v3, v226
	v_or_b32_e32 v7, 10, v197
	v_or_b32_e32 v8, 9, v197
	v_cndmask_b32_e64 v3, v1, 0, vcc
	v_cmp_lt_u32_e32 vcc, v6, v226
	v_or_b32_e32 v9, 11, v197
	v_or_b32_e32 v10, 16, v197
	v_cndmask_b32_e64 v6, v1, 0, vcc
	v_cmp_lt_u32_e32 vcc, v5, v226
	v_or_b32_e32 v12, 17, v197
	v_or_b32_e32 v11, 18, v197
	v_cndmask_b32_e64 v5, v1, 0, vcc
	v_cmp_lt_u32_e32 vcc, v7, v226
	v_or_b32_e32 v14, 19, v197
	v_or_b32_e32 v13, 24, v197
	v_cndmask_b32_e64 v7, v1, 0, vcc
	v_cmp_lt_u32_e32 vcc, v8, v226
	v_or_b32_e32 v15, 26, v197
	v_writelane_b32 v255, s75, 7
	v_cndmask_b32_e64 v8, v1, 0, vcc
	v_cmp_lt_u32_e32 vcc, v9, v226
	v_mul_f32_e32 v0, 0x3f828f5c, v0
	s_mov_b32 s0, 0x42600000
	v_cndmask_b32_e64 v9, v1, 0, vcc
	v_cmp_lt_u32_e32 vcc, v10, v226
	v_or_b32_e32 v16, 25, v197
	v_writelane_b32 v255, s74, 8
	v_cndmask_b32_e64 v10, v1, 0, vcc
	v_cmp_lt_u32_e32 vcc, v12, v226
	v_cmp_ngt_f32_e64 s[0:1], s0, v0
	v_or_b32_e32 v17, 27, v197
	v_cndmask_b32_e64 v12, v1, 0, vcc
	v_cmp_lt_u32_e32 vcc, v11, v226
	v_writelane_b32 v255, s0, 9
	v_and_b32_e32 v18, 16, v241
	v_cndmask_b32_e64 v11, v1, 0, vcc
	v_cmp_lt_u32_e32 vcc, v14, v226
	v_writelane_b32 v255, s1, 10
	s_mov_b32 s0, 0x5040100
	v_cndmask_b32_e64 v14, v1, 0, vcc
	v_cmp_lt_u32_e32 vcc, v13, v226
	v_perm_b32 v96, v4, v2, s0
	v_add_u32_e32 v21, 0x100, v241
	v_cndmask_b32_e64 v13, v1, 0, vcc
	v_cmp_lt_u32_e32 vcc, v15, v226
	v_and_b32_e32 v23, 24, v176
	v_lshl_or_b32 v198, v18, 1, v23
	v_cndmask_b32_e64 v15, v1, 0, vcc
	v_cmp_lt_u32_e32 vcc, v16, v226
	v_lshrrev_b32_e32 v22, 3, v21
	s_load_dwordx8 s[80:87], s[68:69], 0xf8
	v_cndmask_b32_e64 v16, v1, 0, vcc
	v_cmp_lt_u32_e32 vcc, v17, v226
	v_perm_b32 v102, v16, v13, s0
	v_writelane_b32 v255, s68, 11
	v_cndmask_b32_e64 v1, v1, 0, vcc
	v_perm_b32 v103, v1, v15, s0
	v_mul_u32_u24_e32 v1, 0xaaab, v241
	v_lshrrev_b32_e32 v1, 19, v1
	v_mul_lo_u16_e32 v2, 12, v1
	v_mul_u32_u24_e32 v16, 0xd0, v1
	v_sub_u16_e32 v1, v241, v2
	v_lshlrev_b32_e32 v18, 4, v1
	v_mul_u32_u24_e32 v1, 0xaaab, v21
	v_lshrrev_b32_e32 v1, 19, v1
	v_mul_lo_u16_e32 v2, 12, v1
	v_mul_u32_u24_e32 v23, 0xd0, v1
	v_sub_u16_e32 v1, v21, v2
	v_lshlrev_b32_e32 v21, 4, v1
	v_add_u16_e32 v1, 0x200, v241
	v_mul_u32_u24_e32 v2, 0xaaab, v1
	v_lshrrev_b32_e32 v2, 19, v2
	s_load_dwordx8 s[88:95], s[68:69], 0xc0
	v_bfe_u32 v17, v241, 2, 2
	v_perm_b32 v97, v6, v3, s0
	v_mul_lo_u16_e32 v3, 12, v2
	v_mov_b32_e32 v177, 0
	v_or_b32_e32 v17, v197, v17
	v_sub_u16_e32 v1, v1, v3
	v_and_b32_e32 v19, 0x70, v214
	v_mul_u32_u24_e32 v20, 0x90, v232
	v_mul_u32_u24_e32 v22, 0x90, v22
	v_cmp_eq_u32_e64 s[8:9], 0, v179
	v_mul_u32_u24_e32 v200, 0x90, v17
	v_mul_u32_u24_e32 v17, 0x90, v226
	v_perm_b32 v98, v8, v5, s0
	v_perm_b32 v99, v9, v7, s0
	v_perm_b32 v101, v14, v11, s0
	v_perm_b32 v100, v12, v10, s0
	v_mul_u32_u24_e32 v24, 0xd0, v2
	v_lshlrev_b32_e32 v25, 4, v1
	v_xor_b32_e32 v0, 0x80000000, v0
	v_writelane_b32 v255, s69, 12
	v_mov_b32_e32 v179, v177
	s_mov_b32 s0, s76
	v_lshlrev_b32_e32 v196, 5, v254
	s_mov_b32 s5, 0
	v_lshlrev_b32_e32 v199, 2, v254
	v_cmp_eq_u32_e64 s[10:11], 0, v181
	v_and_b32_e32 v201, 0x1e0, v213
	v_mul_u32_u24_e32 v202, 0xd0, v226
	v_mov_b32_e32 v1, v0
	v_mov_b32_e32 v2, v0
	v_mov_b32_e32 v3, v0
	v_mov_b32_e32 v4, v0
	v_mov_b32_e32 v5, v0
	v_mov_b32_e32 v6, v0
	v_mov_b32_e32 v7, v0
	v_mov_b32_e32 v8, v0
	v_mov_b32_e32 v9, v0
	v_mov_b32_e32 v10, v0
	v_mov_b32_e32 v11, v0
	v_mov_b32_e32 v12, v0
	v_mov_b32_e32 v13, v0
	v_mov_b32_e32 v14, v0
	v_mov_b32_e32 v15, v0
	s_waitcnt lgkmcnt(0)
	v_lshl_add_u64 v[172:173], s[80:81], 0, v[178:179]
	v_mov_b32_e32 v179, 0x123f0
	v_mov_b32_e32 v234, 0
	s_movk_i32 s6, 0x2000
	v_lshlrev_b64 v[174:175], 1, v[176:177]
	s_movk_i32 s7, 0x1000
	v_add_u32_e32 v203, v19, v20
	v_add_u32_e32 v204, v19, v22
	s_mov_b32 s96, 0x3f803f80
	s_mov_b32 s76, 0xc2800000
	v_lshlrev_b32_e32 v180, 1, v180
	v_add_u32_e32 v205, v178, v17
	v_add_u32_e32 v206, v16, v18
	v_add_u32_e32 v207, v23, v21
	v_add_u32_e32 v208, v24, v25
	v_mov_b32_e32 v209, 0xc0
	v_mov_b32_e32 v210, 0xff800000
	v_writelane_b32 v255, s0, 13
	s_mov_b32 s2, s0
	s_branch .LBB0_422

; #define AT_LOAD(SET, IT) { const int kl_ = AT_KB(IT); \
;     _Pragma("unroll") for (int i = 0; i < KPT; ++i) kreg[SET][i] = *(const u32x4*)(Kg + (size_t)kl_ * DQK + (tid + 256 * i) * 8); \
;     _Pragma("unroll") for (int i = 0; i < 2; ++i) vreg[SET][i] = *(const u32x4*)(Vg + (size_t)kl_ * 64 + (tid + 256 * i) * 8); \
;     __builtin_amdgcn_sched_barrier(0); }
; template <int DQK, bool SB, bool SMAX>
; DI void attn_item(const Params& p, char* smem, int bh, int qb, float Mb) {
;     ...
;   const int q0 = qb * 128, qw0 = q0 + wave * 32, query = qw0 + r;
;   bf16x8 qf[NKS];
;   {
;     const bf16_t* qp = Qg + ((size_t)bh * S_ + query) * DQK + h * 8;
; #pragma unroll
;     for (int ks = 0; ks < NKS; ++ks) qf[ks] = *(const bf16x8*)(qp + ks * 16);
;   }
;   bf16x8 tri[2], ones;
; #pragma unroll
;   for (int s = 0; s < 2; ++s)
; #pragma unroll
;     for (int j = 0; j < 8; ++j) tri[s][j] = ((16 * s + 8 * (j >> 2) + 4 * h + (j & 3)) >= r) ? (short)0x3F80 : (short)0;
; #pragma unroll
;   for (int j = 0; j < 8; ++j) ones[j] = (short)0x3F80;
;   const int nt = 2 * (qb + 1);
;   f32x16 O[2];
; #pragma unroll
;   for (int db = 0; db < 2; ++db)
; #pragma unroll
;     for (int i = 0; i < 16; ++i) O[db][i] = 0.f;
;   float m = -__builtin_huge_valf(), lsum = 0.f, carry = 0.f;
;   f32x16 negM;
; #pragma unroll
;   for (int i = 0; i < 16; ++i) negM[i] = -Mb;
;   u32x4 kreg[1][KPT], vreg[1][2];
;     ...
;   const int blk = (lane >> 4) & 1, tq = (lane & 15) >> 2, tp = lane & 3;
;   const int voff = (4 * h + tq) * VSTR + 16 * blk + 4 * tp;
;   AT_LOAD(0, 0)
;   AT_WRITE(0, 0)
;   AT_LOAD(0, 1)
;   __syncthreads();
; DI void phase4(const Params& p, char* smem, const Sched sc) {
;     ...
;   for (;;) {
;     if (threadIdx.x == 0) *s_item = (int)atomicAdd(&p.counters[XB_WQ(v)], 1u);
;     __syncthreads();
;     const int item = *s_item;
;     __syncthreads();
;     if (item >= 256) break;
;     if (item < 128) {
;       const int bh = 2 * v + (item & 1), qb = 63 - (item >> 1);
;       if (smax) attn_item<96, false, true>(p, smem, bh, qb, Mb);
;       else attn_item<96, false, false>(p, smem, bh, qb, 0.f);
;     } else { const int j = item - 128; attn_item<64, true, false>(p, smem, 2 * v + (j & 1), 63 - (j >> 1), 0.f); }
.LBB0_427:
	v_add_u32_e32 v233, v179, v234
	s_and_saveexec_b64 s[0:1], s[72:73]
	s_cbranch_execz .LBB0_431
	s_mov_b64 s[12:13], exec
	v_mbcnt_lo_u32_b32 v16, s12, 0
	v_mbcnt_hi_u32_b32 v16, s13, v16
	v_cmp_eq_u32_e32 vcc, 0, v16
	s_and_saveexec_b64 s[2:3], vcc
	s_cbranch_execz .LBB0_430
	s_bcnt1_i32_b64 s4, s[12:13]
	v_readlane_b32 s12, v255, 17
	v_mov_b32_e32 v17, s4
	v_readlane_b32 s13, v255, 18
	s_nop 4
	global_atomic_add v17, v177, v17, s[12:13] sc0
.LBB0_430:
	s_or_b64 exec, exec, s[2:3]
	s_waitcnt vmcnt(0)
	v_readfirstlane_b32 s2, v17
	s_nop 1
	v_add_u32_e32 v16, s2, v16
	ds_write_b32 v233, v16
.LBB0_431:
	s_or_b64 exec, exec, s[0:1]
	s_waitcnt lgkmcnt(0)
	s_barrier
	ds_read_b32 v16, v233
	s_movk_i32 s0, 0xff
	s_waitcnt lgkmcnt(0)
	v_xor_b32_e32 v234, 4, v234
	v_cmp_lt_i32_e32 vcc, s0, v16
	v_readfirstlane_b32 s77, v16
	s_mov_b64 s[0:1], -1
	s_cbranch_vccnz .LBB0_426
	s_cmpk_gt_i32 s77, 0x7f
	s_cbranch_scc0 .LBB0_451
	s_add_i32 s1, s77, 0xffffff80
	s_and_b32 s0, s77, 1
	s_or_b32 s0, s0, s24
	s_lshr_b32 s16, s1, 1
	s_sub_i32 s4, 63, s16
	s_ashr_i32 s1, s0, 31
	v_lshl_add_u32 v153, s4, 7, v196
	s_lshl_b64 s[2:3], s[0:1], 20
	v_or_b32_e32 v176, v153, v226
	s_add_u32 s12, s88, s2
	s_addc_u32 s13, s89, s3
	v_lshlrev_b64 v[16:17], 7, v[176:177]
	v_lshl_add_u64 v[16:17], s[12:13], 0, v[16:17]
	s_add_u32 s12, s90, s2
	s_addc_u32 s13, s91, s3
	s_add_u32 s2, s92, s2
	s_addc_u32 s3, s93, s3
	s_lshl_b32 s17, s4, 14
	s_lshl_b32 s1, s4, 1
	s_or_b32 s4, s17, 0x2000
	v_mov_b32_e32 v181, v177
	s_add_u32 s14, s12, s4
	v_lshl_add_u64 v[16:17], v[16:17], 0, v[180:181]
	s_addc_u32 s15, s13, 0
	global_load_dwordx4 v[104:107], v[16:17], off
	global_load_dwordx4 v[108:111], v[16:17], off offset:32
	global_load_dwordx4 v[112:115], v[16:17], off offset:64
	global_load_dwordx4 v[116:119], v[16:17], off offset:96
	v_lshl_add_u64 v[16:17], s[14:15], 0, v[174:175]
	s_add_u32 s14, s2, s4
	v_add_co_u32_e32 v20, vcc, s7, v16
	s_addc_u32 s15, s3, 0
	s_nop 0
	v_addc_co_u32_e32 v21, vcc, 0, v17, vcc
	v_lshl_add_u64 v[24:25], s[14:15], 0, v[174:175]
	v_add_co_u32_e32 v28, vcc, s7, v24
	global_load_dwordx4 v[16:19], v[16:17], off
	s_nop 0
	global_load_dwordx4 v[20:23], v[20:21], off
	v_addc_co_u32_e32 v29, vcc, 0, v25, vcc
	global_load_dwordx4 v[24:27], v[24:25], off
	s_nop 0
	global_load_dwordx4 v[28:31], v[28:29], off
	s_mov_b32 s79, s24
	s_mov_b32 s4, 0
	s_add_u32 s14, s12, s17
	s_addc_u32 s15, s13, 0
	v_lshl_add_u64 v[32:33], s[14:15], 0, v[174:175]
	s_add_u32 s14, s2, s17
	v_add_co_u32_e32 v34, vcc, s7, v32
	s_addc_u32 s15, s3, 0
	s_nop 0
	v_addc_co_u32_e32 v35, vcc, 0, v33, vcc
	global_load_dwordx4 v[120:123], v[32:33], off
	global_load_dwordx4 v[124:127], v[34:35], off
	v_lshl_add_u64 v[32:33], s[14:15], 0, v[174:175]
	v_add_co_u32_e32 v34, vcc, s7, v32
	s_nop 1
	v_addc_co_u32_e32 v35, vcc, 0, v33, vcc
	global_load_dwordx4 v[128:131], v[32:33], off
	global_load_dwordx4 v[132:135], v[34:35], off
	s_waitcnt vmcnt(7)
	ds_write_b128 v203, v[16:19]
	s_waitcnt vmcnt(6)
	ds_write_b128 v204, v[20:23]
	s_waitcnt vmcnt(5)
	ds_write_b128 v203, v[24:27] offset:18432
	s_waitcnt vmcnt(4)
	ds_write_b128 v204, v[28:31] offset:18432
	v_mov_b32_e32 v30, v177
	v_mov_b32_e32 v31, v177
	v_lshl_add_u64 v[150:151], s[2:3], 0, v[174:175]
	s_lshl_b32 s2, s16, 7
	v_mov_b32_e32 v16, v177
	v_mov_b32_e32 v17, v177
	v_mov_b32_e32 v18, v177
	v_mov_b32_e32 v19, v177
	v_mov_b32_e32 v20, v177
	v_mov_b32_e32 v21, v177
	v_mov_b32_e32 v22, v177
	v_mov_b32_e32 v23, v177
	v_mov_b32_e32 v24, v177
	v_mov_b32_e32 v25, v177
	v_mov_b32_e32 v26, v177
	v_mov_b32_e32 v27, v177
	v_mov_b32_e32 v28, v177
	v_mov_b32_e32 v29, v177
	v_mov_b64_e32 v[46:47], v[30:31]
	v_subrev_u32_e32 v181, 64, v153
	v_lshl_add_u64 v[148:149], s[12:13], 0, v[174:175]
	s_sub_i32 s78, 0x1f40, s2
	v_mov_b32_e32 v152, 0
	v_mov_b64_e32 v[44:45], v[28:29]
	v_mov_b64_e32 v[42:43], v[26:27]
	v_mov_b64_e32 v[40:41], v[24:25]
	v_mov_b64_e32 v[38:39], v[22:23]
	v_mov_b64_e32 v[36:37], v[20:21]
	v_mov_b64_e32 v[34:35], v[18:19]
	v_mov_b64_e32 v[32:33], v[16:17]
	s_waitcnt lgkmcnt(0)
	s_barrier
	s_add_i32 s14, s78, 0x80
	v_cmp_le_i32_e64 s[12:13], s14, v153
	s_and_saveexec_b64 s[2:3], s[12:13]
	s_cbranch_execz .LBB0_435
